# thin GEMM fragment loads de-serialised: all loads of a K sweep issued up front into fresh VGPR quads, counted vmcnt waits
# speedup vs baseline: 1.0015x; 1.0015x over previous
;     ...
;         const bf16* bp0 = Bt + (size_t)(n0 + fr) * K + k0 + 8 * fq; const bf16* bp1 = Bt + (size_t)(n1 + fr) * K + k0 + 8 * fq; const bf16* bp2 = Bt + (size_t)(n2 + fr) * K + k0 + 8 * fq;
;         f32x4 acc[NB][2];
; #pragma unroll
;         for (int j = 0; j < NB; ++j) { acc[j][0] = (f32x4){0.f, 0.f, 0.f, 0.f}; acc[j][1] = (f32x4){0.f, 0.f, 0.f, 0.f}; }
; #pragma unroll UNR
;         for (int s = 0; s < kper; s += 32) {
;             const bf16x8 a0 = *(const bf16x8*)(ap0 + s), a1 = *(const bf16x8*)(ap1 + s), b0 = *(const bf16x8*)(bp0 + s);
;             acc[0][0] = __builtin_amdgcn_mfma_f32_16x16x32_bf16(a0, b0, acc[0][0], 0, 0, 0); acc[0][1] = __builtin_amdgcn_mfma_f32_16x16x32_bf16(a1, b0, acc[0][1], 0, 0, 0);
;             if constexpr (NB > 1) { const bf16x8 b1 = *(const bf16x8*)(bp1 + s), b2 = *(const bf16x8*)(bp2 + s);
;                 acc[1][0] = __builtin_amdgcn_mfma_f32_16x16x32_bf16(a0, b1, acc[1][0], 0, 0, 0); acc[1][1] = __builtin_amdgcn_mfma_f32_16x16x32_bf16(a1, b1, acc[1][1], 0, 0, 0);
;                 acc[2][0] = __builtin_amdgcn_mfma_f32_16x16x32_bf16(a0, b2, acc[2][0], 0, 0, 0); acc[2][1] = __builtin_amdgcn_mfma_f32_16x16x32_bf16(a1, b2, acc[2][1], 0, 0, 0); }
;         }
; #pragma unroll
;         for (int j = 0; j < NB; ++j)
; #pragma unroll
;             for (int r = 0; r < 4; ++r) { red[j * 4096 + F.wave * 512 + (4 * fq + r) * 16 + fr] = acc[j][0][r]; red[j * 4096 + F.wave * 512 + (16 + 4 * fq + r) * 16 + fr] = acc[j][1][r]; }
;         __syncthreads();
; #pragma unroll
;         for (int j = 0; j < NB; ++j) { if (j == 0 || (j == 1 && v1) || (j == 2 && v2)) { float v = 0.f;
; #pragma unroll
;             for (int w = 0; w < 8; ++w) v += red[j * 4096 + w * 512 + F.tid];
;             fn(F.tid >> 4, (j == 0 ? n0 : (j == 1 ? n1 : n2)) + (F.tid & 15), v * rsd); } }
;         __syncthreads();
;     }
; }
.LBB0_148:
	v_ashrrev_i32_e32 v27, 31, v26
	v_lshlrev_b64 v[32:33], 12, v[26:27]
	v_lshl_add_u64 v[52:53], v[6:7], 0, v[32:33]
	global_load_dwordx4 v[40:43], v[2:3], off
	global_load_dwordx4 v[44:47], v[4:5], off
	global_load_dwordx4 v[48:51], v[52:53], off
	global_load_dwordx4 v[54:57], v[2:3], off offset:64
	global_load_dwordx4 v[58:61], v[8:9], off
	global_load_dwordx4 v[62:65], v[52:53], off offset:64
	global_load_dwordx4 v[66:69], v[2:3], off offset:128
	global_load_dwordx4 v[70:73], v[10:11], off
	global_load_dwordx4 v[78:81], v[52:53], off offset:128
	global_load_dwordx4 v[82:85], v[2:3], off offset:192
	global_load_dwordx4 v[86:89], v[12:13], off
	global_load_dwordx4 v[90:93], v[52:53], off offset:192
	global_load_dwordx4 v[94:97], v[2:3], off offset:256
	global_load_dwordx4 v[98:101], v[14:15], off
	global_load_dwordx4 v[102:105], v[52:53], off offset:256
	global_load_dwordx4 v[106:109], v[2:3], off offset:320
	global_load_dwordx4 v[110:113], v[16:17], off
	global_load_dwordx4 v[114:117], v[52:53], off offset:320
	global_load_dwordx4 v[118:121], v[2:3], off offset:384
	global_load_dwordx4 v[122:125], v[18:19], off
	global_load_dwordx4 v[126:129], v[52:53], off offset:384
	global_load_dwordx4 v[130:133], v[2:3], off offset:448
	global_load_dwordx4 v[134:137], v[20:21], off
	global_load_dwordx4 v[138:141], v[52:53], off offset:448
	s_nop 0
	s_nop 0
	s_nop 0
	v_cmp_lt_i32_e32 vcc, s78, v26
	s_nop 0
	s_waitcnt vmcnt(21)
	v_mfma_f32_16x16x32_bf16 v[32:35], v[40:43], v[48:51], 0
	v_mfma_f32_16x16x32_bf16 v[36:39], v[44:47], v[48:51], 0
	s_nop 0
	s_nop 0
	s_nop 0
	s_nop 0
	s_waitcnt vmcnt(18)
	v_mfma_f32_16x16x32_bf16 v[32:35], v[54:57], v[62:65], v[32:35]
	v_mfma_f32_16x16x32_bf16 v[36:39], v[58:61], v[62:65], v[36:39]
	s_nop 0
	s_nop 0
	s_nop 0
	s_nop 0
	s_waitcnt vmcnt(15)
	v_mfma_f32_16x16x32_bf16 v[32:35], v[66:69], v[78:81], v[32:35]
	v_mfma_f32_16x16x32_bf16 v[36:39], v[70:73], v[78:81], v[36:39]
	s_nop 0
	s_nop 0
	s_nop 0
	s_nop 0
	s_waitcnt vmcnt(12)
	v_mfma_f32_16x16x32_bf16 v[32:35], v[82:85], v[90:93], v[32:35]
	v_mfma_f32_16x16x32_bf16 v[36:39], v[86:89], v[90:93], v[36:39]
	s_nop 0
	s_nop 0
	s_nop 0
	s_nop 0
	s_waitcnt vmcnt(9)
	v_mfma_f32_16x16x32_bf16 v[32:35], v[94:97], v[102:105], v[32:35]
	v_mfma_f32_16x16x32_bf16 v[36:39], v[98:101], v[102:105], v[36:39]
	s_nop 0
	s_nop 0
	s_nop 0
	s_nop 0
	s_waitcnt vmcnt(6)
	v_mfma_f32_16x16x32_bf16 v[32:35], v[106:109], v[114:117], v[32:35]
	v_mfma_f32_16x16x32_bf16 v[36:39], v[110:113], v[114:117], v[36:39]
	s_nop 0
	s_nop 0
	s_nop 0
	s_nop 0
	s_waitcnt vmcnt(3)
	v_mfma_f32_16x16x32_bf16 v[32:35], v[118:121], v[126:129], v[32:35]
	v_mfma_f32_16x16x32_bf16 v[36:39], v[122:125], v[126:129], v[36:39]
	s_nop 0
	s_nop 0
	s_nop 0
	s_nop 0
	s_waitcnt vmcnt(0)
	v_mfma_f32_16x16x32_bf16 v[32:35], v[130:133], v[138:141], v[32:35]
	v_mfma_f32_16x16x32_bf16 v[36:39], v[134:137], v[138:141], v[36:39]
	s_nop 6
	ds_write2_b32 v29, v32, v33 offset1:16
	ds_write2_b32 v30, v36, v37 offset1:16
	ds_write2_b32 v29, v34, v35 offset0:32 offset1:48
	ds_write2_b32 v30, v38, v39 offset0:32 offset1:48
	s_waitcnt lgkmcnt(0)
	s_barrier
	ds_read2st64_b32 v[32:33], v0 offset1:8
	s_waitcnt lgkmcnt(0)
	v_add_f32_e32 v31, 0, v32
	v_add_f32_e32 v31, v31, v33
	ds_read2st64_b32 v[32:33], v0 offset0:16 offset1:24
	s_waitcnt lgkmcnt(0)
	v_add_f32_e32 v31, v31, v32
	v_add_f32_e32 v31, v31, v33
	ds_read2st64_b32 v[32:33], v0 offset0:32 offset1:40
	s_waitcnt lgkmcnt(0)
	v_add_f32_e32 v31, v31, v32
	v_add_f32_e32 v31, v31, v33
	ds_read2st64_b32 v[32:33], v0 offset0:48 offset1:56
	s_waitcnt lgkmcnt(0)
	v_add_f32_e32 v31, v31, v32
	v_add_f32_e32 v34, v31, v33
	v_lshl_add_u64 v[32:33], v[26:27], 2, s[0:1]
	global_load_dword v31, v[32:33], off
	s_waitcnt vmcnt(0)
	v_fmac_f32_e32 v31, v28, v34
	s_and_saveexec_b64 s[10:11], vcc
	s_xor_b64 s[10:11], exec, s[10:11]
	s_cbranch_execz .LBB0_150
	v_cvt_pk_bf16_f32 v31, v31, v1
	v_lshl_add_u64 v[32:33], v[26:27], 1, v[22:23]
	global_store_short v[32:33], v31, off offset:-4096

;     ...
;         const bf16* bp0 = Bt + (size_t)(n0 + fr) * K + k0 + 8 * fq; const bf16* bp1 = Bt + (size_t)(n1 + fr) * K + k0 + 8 * fq; const bf16* bp2 = Bt + (size_t)(n2 + fr) * K + k0 + 8 * fq;
;         f32x4 acc[NB][2];
; #pragma unroll
;         for (int j = 0; j < NB; ++j) { acc[j][0] = (f32x4){0.f, 0.f, 0.f, 0.f}; acc[j][1] = (f32x4){0.f, 0.f, 0.f, 0.f}; }
; #pragma unroll UNR
;         for (int s = 0; s < kper; s += 32) {
;             const bf16x8 a0 = *(const bf16x8*)(ap0 + s), a1 = *(const bf16x8*)(ap1 + s), b0 = *(const bf16x8*)(bp0 + s);
;             acc[0][0] = __builtin_amdgcn_mfma_f32_16x16x32_bf16(a0, b0, acc[0][0], 0, 0, 0); acc[0][1] = __builtin_amdgcn_mfma_f32_16x16x32_bf16(a1, b0, acc[0][1], 0, 0, 0);
;             if constexpr (NB > 1) { const bf16x8 b1 = *(const bf16x8*)(bp1 + s), b2 = *(const bf16x8*)(bp2 + s);
;                 acc[1][0] = __builtin_amdgcn_mfma_f32_16x16x32_bf16(a0, b1, acc[1][0], 0, 0, 0); acc[1][1] = __builtin_amdgcn_mfma_f32_16x16x32_bf16(a1, b1, acc[1][1], 0, 0, 0);
;                 acc[2][0] = __builtin_amdgcn_mfma_f32_16x16x32_bf16(a0, b2, acc[2][0], 0, 0, 0); acc[2][1] = __builtin_amdgcn_mfma_f32_16x16x32_bf16(a1, b2, acc[2][1], 0, 0, 0); }
;         }
; #pragma unroll
;         for (int j = 0; j < NB; ++j)
; #pragma unroll
;             for (int r = 0; r < 4; ++r) { red[j * 4096 + F.wave * 512 + (4 * fq + r) * 16 + fr] = acc[j][0][r]; red[j * 4096 + F.wave * 512 + (16 + 4 * fq + r) * 16 + fr] = acc[j][1][r]; }
;         __syncthreads();
; #pragma unroll
;         for (int j = 0; j < NB; ++j) { if (j == 0 || (j == 1 && v1) || (j == 2 && v2)) { float v = 0.f;
; #pragma unroll
;             for (int w = 0; w < 8; ++w) v += red[j * 4096 + w * 512 + F.tid];
;             fn(F.tid >> 4, (j == 0 ? n0 : (j == 1 ? n1 : n2)) + (F.tid & 15), v * rsd); } }
;         __syncthreads();
;     }
; }
.LBB0_644:
	v_ashrrev_i32_e32 v27, 31, v26
	v_lshlrev_b64 v[28:29], 12, v[26:27]
	v_lshl_add_u64 v[36:37], v[6:7], 0, v[28:29]
	global_load_dwordx4 v[40:43], v[2:3], off
	global_load_dwordx4 v[44:47], v[4:5], off
	global_load_dwordx4 v[48:51], v[36:37], off
	global_load_dwordx4 v[52:55], v[2:3], off offset:64
	global_load_dwordx4 v[56:59], v[10:11], off
	global_load_dwordx4 v[60:63], v[36:37], off offset:64
	global_load_dwordx4 v[64:67], v[2:3], off offset:128
	global_load_dwordx4 v[68:71], v[12:13], off
	global_load_dwordx4 v[78:81], v[36:37], off offset:128
	global_load_dwordx4 v[82:85], v[2:3], off offset:192
	global_load_dwordx4 v[86:89], v[14:15], off
	global_load_dwordx4 v[90:93], v[36:37], off offset:192
	global_load_dwordx4 v[94:97], v[2:3], off offset:256
	global_load_dwordx4 v[98:101], v[16:17], off
	global_load_dwordx4 v[102:105], v[36:37], off offset:256
	global_load_dwordx4 v[106:109], v[2:3], off offset:320
	global_load_dwordx4 v[110:113], v[18:19], off
	global_load_dwordx4 v[114:117], v[36:37], off offset:320
	global_load_dwordx4 v[118:121], v[2:3], off offset:384
	global_load_dwordx4 v[122:125], v[20:21], off
	global_load_dwordx4 v[126:129], v[36:37], off offset:384
	global_load_dwordx4 v[130:133], v[2:3], off offset:448
	global_load_dwordx4 v[134:137], v[22:23], off
	global_load_dwordx4 v[138:141], v[36:37], off offset:448
	s_nop 0
	s_nop 0
	s_nop 0
	s_andn2_b64 vcc, exec, s[0:1]
	s_nop 0
	s_waitcnt vmcnt(21)
	v_mfma_f32_16x16x32_bf16 v[28:31], v[40:43], v[48:51], 0
	v_mfma_f32_16x16x32_bf16 v[32:35], v[44:47], v[48:51], 0
	s_nop 0
	s_nop 0
	s_nop 0
	s_nop 0
	s_waitcnt vmcnt(18)
	v_mfma_f32_16x16x32_bf16 v[28:31], v[52:55], v[60:63], v[28:31]
	v_mfma_f32_16x16x32_bf16 v[32:35], v[56:59], v[60:63], v[32:35]
	s_nop 0
	s_nop 0
	s_nop 0
	s_nop 0
	s_waitcnt vmcnt(15)
	v_mfma_f32_16x16x32_bf16 v[28:31], v[64:67], v[78:81], v[28:31]
	v_mfma_f32_16x16x32_bf16 v[32:35], v[68:71], v[78:81], v[32:35]
	s_nop 0
	s_nop 0
	s_nop 0
	s_nop 0
	s_waitcnt vmcnt(12)
	v_mfma_f32_16x16x32_bf16 v[28:31], v[82:85], v[90:93], v[28:31]
	v_mfma_f32_16x16x32_bf16 v[32:35], v[86:89], v[90:93], v[32:35]
	s_nop 0
	s_nop 0
	s_nop 0
	s_nop 0
	s_waitcnt vmcnt(9)
	v_mfma_f32_16x16x32_bf16 v[28:31], v[94:97], v[102:105], v[28:31]
	v_mfma_f32_16x16x32_bf16 v[32:35], v[98:101], v[102:105], v[32:35]
	s_nop 0
	s_nop 0
	s_nop 0
	s_nop 0
	s_waitcnt vmcnt(6)
	v_mfma_f32_16x16x32_bf16 v[28:31], v[106:109], v[114:117], v[28:31]
	v_mfma_f32_16x16x32_bf16 v[32:35], v[110:113], v[114:117], v[32:35]
	s_nop 0
	s_nop 0
	s_nop 0
	s_nop 0
	s_waitcnt vmcnt(3)
	v_mfma_f32_16x16x32_bf16 v[28:31], v[118:121], v[126:129], v[28:31]
	v_mfma_f32_16x16x32_bf16 v[32:35], v[122:125], v[126:129], v[32:35]
	s_nop 0
	s_nop 0
	s_nop 0
	v_lshl_add_u64 v[36:37], v[26:27], 1, v[8:9]
	s_nop 0
	s_waitcnt vmcnt(0)
	v_mfma_f32_16x16x32_bf16 v[28:31], v[130:133], v[138:141], v[28:31]
	s_nop 7
	ds_write2_b32 v38, v28, v29 offset1:16
	v_mfma_f32_16x16x32_bf16 v[32:35], v[134:137], v[138:141], v[32:35]
	v_add_u32_e32 v28, 0x400, v38
	s_nop 6
	ds_write2_b32 v28, v32, v33 offset1:16
	ds_write2_b32 v38, v30, v31 offset0:32 offset1:48
	ds_write2_b32 v28, v34, v35 offset0:32 offset1:48
	s_waitcnt lgkmcnt(0)
	s_barrier
	ds_read2st64_b32 v[34:35], v0 offset1:8
	ds_read2st64_b32 v[32:33], v0 offset0:16 offset1:24
	ds_read2st64_b32 v[30:31], v0 offset0:32 offset1:40
	ds_read2st64_b32 v[28:29], v0 offset0:48 offset1:56
	global_load_ushort v39, v[36:37], off
	s_cbranch_vccnz .LBB0_646
	v_lshl_add_u64 v[40:41], v[26:27], 2, s[24:25]
	global_load_dword v27, v[40:41], off
	s_branch .LBB0_647

;     ...
;         const bf16* bp0 = Bt + (size_t)(n0 + fr) * K + k0 + 8 * fq; const bf16* bp1 = Bt + (size_t)(n1 + fr) * K + k0 + 8 * fq; const bf16* bp2 = Bt + (size_t)(n2 + fr) * K + k0 + 8 * fq;
;         f32x4 acc[NB][2];
; #pragma unroll
;         for (int j = 0; j < NB; ++j) { acc[j][0] = (f32x4){0.f, 0.f, 0.f, 0.f}; acc[j][1] = (f32x4){0.f, 0.f, 0.f, 0.f}; }
; #pragma unroll UNR
;         for (int s = 0; s < kper; s += 32) {
;             const bf16x8 a0 = *(const bf16x8*)(ap0 + s), a1 = *(const bf16x8*)(ap1 + s), b0 = *(const bf16x8*)(bp0 + s);
;             acc[0][0] = __builtin_amdgcn_mfma_f32_16x16x32_bf16(a0, b0, acc[0][0], 0, 0, 0); acc[0][1] = __builtin_amdgcn_mfma_f32_16x16x32_bf16(a1, b0, acc[0][1], 0, 0, 0);
;             if constexpr (NB > 1) { const bf16x8 b1 = *(const bf16x8*)(bp1 + s), b2 = *(const bf16x8*)(bp2 + s);
;                 acc[1][0] = __builtin_amdgcn_mfma_f32_16x16x32_bf16(a0, b1, acc[1][0], 0, 0, 0); acc[1][1] = __builtin_amdgcn_mfma_f32_16x16x32_bf16(a1, b1, acc[1][1], 0, 0, 0);
;                 acc[2][0] = __builtin_amdgcn_mfma_f32_16x16x32_bf16(a0, b2, acc[2][0], 0, 0, 0); acc[2][1] = __builtin_amdgcn_mfma_f32_16x16x32_bf16(a1, b2, acc[2][1], 0, 0, 0); }
;         }
.LBB0_760:
	s_add_i32 s24, s25, s54
	s_add_i32 s27, s17, s25
	s_cmpk_lt_i32 s24, 0x300
	s_cselect_b32 s2, s24, s25
	s_lshl_b32 s26, s2, 4
	s_cmpk_lt_i32 s27, 0x300
	s_cselect_b64 s[2:3], -1, 0
	s_and_b64 s[28:29], s[2:3], exec
	s_cselect_b32 s25, s27, s25
	s_lshl_b32 s25, s25, 4
	v_or_b32_e32 v26, s26, v30
	v_add_u32_e32 v24, s16, v30
	v_ashrrev_i32_e32 v27, 31, v26
	v_or_b32_e32 v28, s25, v30
	v_ashrrev_i32_e32 v25, 31, v24
	v_lshlrev_b64 v[26:27], 12, v[26:27]
	v_ashrrev_i32_e32 v29, 31, v28
	v_lshlrev_b64 v[24:25], 12, v[24:25]
	v_lshlrev_b64 v[34:35], 12, v[28:29]
	v_lshl_add_u64 v[26:27], v[6:7], 0, v[26:27]
	v_lshl_add_u64 v[28:29], v[6:7], 0, v[24:25]
	v_lshl_add_u64 v[24:25], v[6:7], 0, v[34:35]
	global_load_dwordx4 v[54:57], v[2:3], off
	global_load_dwordx4 v[62:65], v[4:5], off
	global_load_dwordx4 v[66:69], v[28:29], off
	global_load_dwordx4 v[70:73], v[26:27], off
	global_load_dwordx4 v[78:81], v[24:25], off
	global_load_dwordx4 v[82:85], v[2:3], off offset:64
	global_load_dwordx4 v[86:89], v[8:9], off
	global_load_dwordx4 v[90:93], v[28:29], off offset:64
	global_load_dwordx4 v[94:97], v[26:27], off offset:64
	global_load_dwordx4 v[98:101], v[24:25], off offset:64
	global_load_dwordx4 v[102:105], v[2:3], off offset:128
	global_load_dwordx4 v[106:109], v[10:11], off
	global_load_dwordx4 v[110:113], v[28:29], off offset:128
	global_load_dwordx4 v[114:117], v[26:27], off offset:128
	global_load_dwordx4 v[118:121], v[24:25], off offset:128
	global_load_dwordx4 v[122:125], v[2:3], off offset:192
	global_load_dwordx4 v[126:129], v[12:13], off
	global_load_dwordx4 v[130:133], v[28:29], off offset:192
	global_load_dwordx4 v[134:137], v[26:27], off offset:192
	global_load_dwordx4 v[138:141], v[24:25], off offset:192
	global_load_dwordx4 v[142:145], v[2:3], off offset:256
	global_load_dwordx4 v[146:149], v[14:15], off
	global_load_dwordx4 v[150:153], v[28:29], off offset:256
	global_load_dwordx4 v[154:157], v[26:27], off offset:256
	global_load_dwordx4 v[158:161], v[24:25], off offset:256
	global_load_dwordx4 v[162:165], v[2:3], off offset:320
	global_load_dwordx4 v[170:173], v[16:17], off
	global_load_dwordx4 v[176:179], v[28:29], off offset:320
	global_load_dwordx4 v[190:193], v[26:27], off offset:320
	global_load_dwordx4 v[196:199], v[24:25], off offset:320
	global_load_dwordx4 v[200:203], v[2:3], off offset:384
	global_load_dwordx4 v[204:207], v[18:19], off
	global_load_dwordx4 v[208:211], v[28:29], off offset:384
	global_load_dwordx4 v[212:215], v[26:27], off offset:384
	global_load_dwordx4 v[216:219], v[24:25], off offset:384
	global_load_dwordx4 v[228:231], v[2:3], off offset:448
	global_load_dwordx4 v[232:235], v[20:21], off
	global_load_dwordx4 v[236:239], v[28:29], off offset:448
	global_load_dwordx4 v[240:243], v[26:27], off offset:448
	global_load_dwordx4 v[244:247], v[24:25], off offset:448
	s_nop 0
	s_nop 0
	s_nop 0
	s_nop 0
	s_nop 0
	s_and_b32 s27, s16, 0xf0
	s_cmpk_lt_u32 s27, 0x80
	s_cselect_b64 vcc, -1, 0
	s_and_b32 s28, s12, 0xffffff80
	s_add_i32 s29, s28, 0x1780
	s_cmpk_gt_i32 s24, 0x2ff
	s_nop 0
	s_waitcnt vmcnt(36)
	v_mfma_f32_16x16x32_bf16 v[58:61], v[54:57], v[70:73], 0
	v_mfma_f32_16x16x32_bf16 v[46:49], v[54:57], v[66:69], 0
	v_mfma_f32_16x16x32_bf16 v[42:45], v[62:65], v[66:69], 0
	v_mfma_f32_16x16x32_bf16 v[50:53], v[62:65], v[70:73], 0
	s_nop 0
	s_waitcnt vmcnt(35)
	v_mfma_f32_16x16x32_bf16 v[34:37], v[54:57], v[78:81], 0
	v_mfma_f32_16x16x32_bf16 v[38:41], v[62:65], v[78:81], 0
	s_nop 0
	s_nop 0
	s_nop 0
	s_nop 0
	s_waitcnt vmcnt(32)
	v_mfma_f32_16x16x32_bf16 v[46:49], v[82:85], v[90:93], v[46:49]
	v_mfma_f32_16x16x32_bf16 v[42:45], v[86:89], v[90:93], v[42:45]
	s_nop 0
	s_nop 0
	s_nop 0
	s_waitcnt vmcnt(31)
	v_mfma_f32_16x16x32_bf16 v[58:61], v[82:85], v[94:97], v[58:61]
	v_mfma_f32_16x16x32_bf16 v[50:53], v[86:89], v[94:97], v[50:53]
	s_nop 0
	s_waitcnt vmcnt(30)
	v_mfma_f32_16x16x32_bf16 v[34:37], v[82:85], v[98:101], v[34:37]
	v_mfma_f32_16x16x32_bf16 v[38:41], v[86:89], v[98:101], v[38:41]
	s_nop 0
	s_nop 0
	s_nop 0
	s_nop 0
	s_waitcnt vmcnt(27)
	v_mfma_f32_16x16x32_bf16 v[46:49], v[102:105], v[110:113], v[46:49]
	v_mfma_f32_16x16x32_bf16 v[42:45], v[106:109], v[110:113], v[42:45]
	s_nop 0
	s_nop 0
	s_nop 0
	s_waitcnt vmcnt(26)
	v_mfma_f32_16x16x32_bf16 v[58:61], v[102:105], v[114:117], v[58:61]
	v_mfma_f32_16x16x32_bf16 v[50:53], v[106:109], v[114:117], v[50:53]
	s_nop 0
	s_waitcnt vmcnt(25)
	v_mfma_f32_16x16x32_bf16 v[34:37], v[102:105], v[118:121], v[34:37]
	v_mfma_f32_16x16x32_bf16 v[38:41], v[106:109], v[118:121], v[38:41]
	s_nop 0
	s_nop 0
	s_nop 0
	s_nop 0
	s_waitcnt vmcnt(22)
	v_mfma_f32_16x16x32_bf16 v[46:49], v[122:125], v[130:133], v[46:49]
	v_mfma_f32_16x16x32_bf16 v[42:45], v[126:129], v[130:133], v[42:45]
	s_nop 0
	s_nop 0
	s_nop 0
	s_waitcnt vmcnt(21)
	v_mfma_f32_16x16x32_bf16 v[58:61], v[122:125], v[134:137], v[58:61]
	v_mfma_f32_16x16x32_bf16 v[50:53], v[126:129], v[134:137], v[50:53]
	s_nop 0
	s_waitcnt vmcnt(20)
;     ...
;         for (int s = 0; s < kper; s += 32) {
;             const bf16x8 a0 = *(const bf16x8*)(ap0 + s), a1 = *(const bf16x8*)(ap1 + s), b0 = *(const bf16x8*)(bp0 + s);
;             acc[0][0] = __builtin_amdgcn_mfma_f32_16x16x32_bf16(a0, b0, acc[0][0], 0, 0, 0); acc[0][1] = __builtin_amdgcn_mfma_f32_16x16x32_bf16(a1, b0, acc[0][1], 0, 0, 0);
;             if constexpr (NB > 1) { const bf16x8 b1 = *(const bf16x8*)(bp1 + s), b2 = *(const bf16x8*)(bp2 + s);
;                 acc[1][0] = __builtin_amdgcn_mfma_f32_16x16x32_bf16(a0, b1, acc[1][0], 0, 0, 0); acc[1][1] = __builtin_amdgcn_mfma_f32_16x16x32_bf16(a1, b1, acc[1][1], 0, 0, 0);
;                 acc[2][0] = __builtin_amdgcn_mfma_f32_16x16x32_bf16(a0, b2, acc[2][0], 0, 0, 0); acc[2][1] = __builtin_amdgcn_mfma_f32_16x16x32_bf16(a1, b2, acc[2][1], 0, 0, 0); }
;         }
; #pragma unroll
;         for (int j = 0; j < NB; ++j)
; #pragma unroll
;             for (int r = 0; r < 4; ++r) { red[j * 4096 + F.wave * 512 + (4 * fq + r) * 16 + fr] = acc[j][0][r]; red[j * 4096 + F.wave * 512 + (16 + 4 * fq + r) * 16 + fr] = acc[j][1][r]; }
;         __syncthreads();
; #pragma unroll
;         for (int j = 0; j < NB; ++j) { if (j == 0 || (j == 1 && v1) || (j == 2 && v2)) { float v = 0.f;
; #pragma unroll
;             for (int w = 0; w < 8; ++w) v += red[j * 4096 + w * 512 + F.tid];
;             fn(F.tid >> 4, (j == 0 ? n0 : (j == 1 ? n1 : n2)) + (F.tid & 15), v * rsd); } }
	v_mfma_f32_16x16x32_bf16 v[34:37], v[122:125], v[138:141], v[34:37]
	v_mfma_f32_16x16x32_bf16 v[38:41], v[126:129], v[138:141], v[38:41]
	s_nop 0
	s_nop 0
	s_nop 0
	s_nop 0
	s_waitcnt vmcnt(17)
	v_mfma_f32_16x16x32_bf16 v[46:49], v[142:145], v[150:153], v[46:49]
	v_mfma_f32_16x16x32_bf16 v[42:45], v[146:149], v[150:153], v[42:45]
	s_nop 0
	s_nop 0
	s_nop 0
	s_waitcnt vmcnt(16)
	v_mfma_f32_16x16x32_bf16 v[58:61], v[142:145], v[154:157], v[58:61]
	v_mfma_f32_16x16x32_bf16 v[50:53], v[146:149], v[154:157], v[50:53]
	s_nop 0
	s_waitcnt vmcnt(15)
	v_mfma_f32_16x16x32_bf16 v[34:37], v[142:145], v[158:161], v[34:37]
	v_mfma_f32_16x16x32_bf16 v[38:41], v[146:149], v[158:161], v[38:41]
	s_nop 0
	s_nop 0
	s_nop 0
	s_nop 0
	s_waitcnt vmcnt(12)
	v_mfma_f32_16x16x32_bf16 v[46:49], v[162:165], v[176:179], v[46:49]
	v_mfma_f32_16x16x32_bf16 v[42:45], v[170:173], v[176:179], v[42:45]
	s_nop 0
	s_nop 0
	s_nop 0
	s_waitcnt vmcnt(11)
	v_mfma_f32_16x16x32_bf16 v[58:61], v[162:165], v[190:193], v[58:61]
	v_mfma_f32_16x16x32_bf16 v[50:53], v[170:173], v[190:193], v[50:53]
	s_nop 0
	s_waitcnt vmcnt(10)
	v_mfma_f32_16x16x32_bf16 v[34:37], v[162:165], v[196:199], v[34:37]
	v_mfma_f32_16x16x32_bf16 v[38:41], v[170:173], v[196:199], v[38:41]
	s_nop 0
	s_nop 0
	s_nop 0
	s_nop 0
	s_waitcnt vmcnt(7)
	v_mfma_f32_16x16x32_bf16 v[46:49], v[200:203], v[208:211], v[46:49]
	v_mfma_f32_16x16x32_bf16 v[42:45], v[204:207], v[208:211], v[42:45]
	s_nop 0
	s_nop 0
	s_nop 0
	s_waitcnt vmcnt(6)
	v_mfma_f32_16x16x32_bf16 v[58:61], v[200:203], v[212:215], v[58:61]
	v_mfma_f32_16x16x32_bf16 v[50:53], v[204:207], v[212:215], v[50:53]
	s_nop 0
	s_waitcnt vmcnt(5)
	v_mfma_f32_16x16x32_bf16 v[34:37], v[200:203], v[216:219], v[34:37]
	v_mfma_f32_16x16x32_bf16 v[38:41], v[204:207], v[216:219], v[38:41]
	s_nop 0
	s_nop 0
	s_nop 0
	s_nop 0
	s_waitcnt vmcnt(2)
	v_mfma_f32_16x16x32_bf16 v[46:49], v[228:231], v[236:239], v[46:49]
	v_mfma_f32_16x16x32_bf16 v[42:45], v[232:235], v[236:239], v[42:45]
	s_nop 0
	s_nop 0
	s_nop 0
	s_nop 3
	ds_write2_b32 v32, v46, v47 offset1:16
	s_nop 0
	s_waitcnt vmcnt(1)
	v_mfma_f32_16x16x32_bf16 v[58:61], v[228:231], v[240:243], v[58:61]
	v_mfma_f32_16x16x32_bf16 v[24:27], v[232:235], v[240:243], v[50:53]
	v_add_u32_e32 v28, 0x400, v32
	ds_write2_b32 v28, v42, v43 offset1:16
	ds_write2_b32 v32, v48, v49 offset0:32 offset1:48
	ds_write2_b32 v28, v44, v45 offset0:32 offset1:48
	v_add_u32_e32 v28, 0x4000, v32
	s_nop 0
	s_waitcnt vmcnt(0)
	v_mfma_f32_16x16x32_bf16 v[34:37], v[228:231], v[244:247], v[34:37]
	v_add_u32_e32 v29, 0x4400, v32
	ds_write2_b32 v28, v58, v59 offset1:16
	ds_write2_b32 v29, v24, v25 offset1:16
	ds_write2_b32 v28, v60, v61 offset0:32 offset1:48
	ds_write2_b32 v29, v26, v27 offset0:32 offset1:48
	v_mfma_f32_16x16x32_bf16 v[38:41], v[232:235], v[244:247], v[38:41]
	v_add_u32_e32 v24, 0x8000, v32
	v_add_u32_e32 v25, 0x8400, v32
	ds_write2_b32 v24, v34, v35 offset1:16
	s_nop 4
	ds_write2_b32 v25, v38, v39 offset1:16
	ds_write2_b32 v24, v36, v37 offset0:32 offset1:48
	ds_write2_b32 v25, v40, v41 offset0:32 offset1:48
	s_waitcnt lgkmcnt(0)
	s_barrier
	ds_read2st64_b32 v[24:25], v0 offset1:8
	s_waitcnt lgkmcnt(0)
	v_add_f32_e32 v24, 0, v24
	v_add_f32_e32 v26, v24, v25
	ds_read2st64_b32 v[24:25], v0 offset0:16 offset1:24
	s_waitcnt lgkmcnt(0)
	v_add_f32_e32 v24, v26, v24
	v_add_f32_e32 v26, v24, v25
	ds_read2st64_b32 v[24:25], v0 offset0:32 offset1:40
	s_waitcnt lgkmcnt(0)
	v_add_f32_e32 v24, v26, v24
	v_add_f32_e32 v26, v24, v25
	ds_read2st64_b32 v[24:25], v0 offset0:48 offset1:56
	s_waitcnt lgkmcnt(0)
	v_add_f32_e32 v24, v26, v24
	v_add_f32_e32 v24, v24, v25
	v_mul_f32_e32 v25, v31, v24
	v_or_b32_e32 v24, s27, v30
	v_or_b32_e32 v26, s28, v24
	v_add_u32_e32 v24, s29, v24
	v_cndmask_b32_e32 v24, v24, v26, vcc
	v_cvt_pk_bf16_f32 v26, v25, v1
	v_ashrrev_i32_e32 v25, 31, v24
	v_lshl_add_u64 v[24:25], v[24:25], 1, v[22:23]
	global_store_short v[24:25], v26, off
	s_cbranch_scc1 .LBB0_762
	ds_read2st64_b32 v[24:25], v0 offset0:64 offset1:72
	s_and_b32 s26, s26, 0xf0
	s_cmpk_lt_u32 s26, 0x80
	s_cselect_b64 vcc, -1, 0
	s_waitcnt lgkmcnt(0)
	v_add_f32_e32 v24, 0, v24
	v_add_f32_e32 v26, v24, v25
	ds_read2st64_b32 v[24:25], v0 offset0:80 offset1:88
	s_waitcnt lgkmcnt(0)
	v_add_f32_e32 v24, v26, v24
	v_add_f32_e32 v26, v24, v25
	ds_read2st64_b32 v[24:25], v0 offset0:96 offset1:104
	s_waitcnt lgkmcnt(0)
	v_add_f32_e32 v24, v26, v24
	v_add_f32_e32 v26, v24, v25
	ds_read2st64_b32 v[24:25], v0 offset0:112 offset1:120
	s_waitcnt lgkmcnt(0)
	v_add_f32_e32 v24, v26, v24
	v_add_f32_e32 v24, v24, v25
	v_mul_f32_e32 v25, v31, v24
	v_or_b32_e32 v24, s26, v30
	s_add_i32 s26, s19, s12
	s_and_b32 s26, s26, 0xffffff80
	v_or_b32_e32 v26, s26, v24
	s_addk_i32 s26, 0x1780
	v_add_u32_e32 v24, s26, v24
	v_cndmask_b32_e32 v24, v24, v26, vcc
	v_cvt_pk_bf16_f32 v26, v25, v1
	v_ashrrev_i32_e32 v25, 31, v24
	v_lshl_add_u64 v[24:25], v[24:25], 1, v[22:23]
	global_store_short v[24:25], v26, off

;     ...
; #pragma unroll UNR
;         for (int s = 0; s < kper; s += 32) {
;             const bf16x8 a0 = *(const bf16x8*)(ap0 + s), a1 = *(const bf16x8*)(ap1 + s), b0 = *(const bf16x8*)(bp0 + s);
;             acc[0][0] = __builtin_amdgcn_mfma_f32_16x16x32_bf16(a0, b0, acc[0][0], 0, 0, 0); acc[0][1] = __builtin_amdgcn_mfma_f32_16x16x32_bf16(a1, b0, acc[0][1], 0, 0, 0);
;             if constexpr (NB > 1) { const bf16x8 b1 = *(const bf16x8*)(bp1 + s), b2 = *(const bf16x8*)(bp2 + s);
;                 acc[1][0] = __builtin_amdgcn_mfma_f32_16x16x32_bf16(a0, b1, acc[1][0], 0, 0, 0); acc[1][1] = __builtin_amdgcn_mfma_f32_16x16x32_bf16(a1, b1, acc[1][1], 0, 0, 0);
;                 acc[2][0] = __builtin_amdgcn_mfma_f32_16x16x32_bf16(a0, b2, acc[2][0], 0, 0, 0); acc[2][1] = __builtin_amdgcn_mfma_f32_16x16x32_bf16(a1, b2, acc[2][1], 0, 0, 0); }
;         }
; #pragma unroll
;         for (int j = 0; j < NB; ++j)
; #pragma unroll
;             for (int r = 0; r < 4; ++r) { red[j * 4096 + F.wave * 512 + (4 * fq + r) * 16 + fr] = acc[j][0][r]; red[j * 4096 + F.wave * 512 + (16 + 4 * fq + r) * 16 + fr] = acc[j][1][r]; }
;         __syncthreads();
; #pragma unroll
;         for (int j = 0; j < NB; ++j) { if (j == 0 || (j == 1 && v1) || (j == 2 && v2)) { float v = 0.f;
; #pragma unroll
;             for (int w = 0; w < 8; ++w) v += red[j * 4096 + w * 512 + F.tid];
;             fn(F.tid >> 4, (j == 0 ? n0 : (j == 1 ? n1 : n2)) + (F.tid & 15), v * rsd); } }
;         __syncthreads();
;     }
; }
.LBB0_939:
	v_lshl_add_u64 v[20:21], v[18:19], 0, v[0:1]
	v_add_co_u32_e32 v22, vcc, 0x32c00000, v20
	s_nop 1
	v_addc_co_u32_e32 v23, vcc, 0, v21, vcc
	v_add_co_u32_e32 v24, vcc, 0x32c30000, v20
	global_load_dwordx4 v[32:35], v[22:23], off
	s_nop 0
	s_nop 0
	v_addc_co_u32_e32 v25, vcc, 0, v21, vcc
	global_load_dwordx4 v[36:39], v[24:25], off
	s_nop 0
	v_lshl_add_u64 v[20:21], v[18:19], 0, v[16:17]
	global_load_dwordx4 v[40:43], v[20:21], off offset:-384
	global_load_dwordx4 v[44:47], v[22:23], off offset:64
	global_load_dwordx4 v[48:51], v[24:25], off offset:64
	global_load_dwordx4 v[52:55], v[20:21], off offset:-320
	global_load_dwordx4 v[56:59], v[22:23], off offset:128
	global_load_dwordx4 v[60:63], v[24:25], off offset:128
	global_load_dwordx4 v[64:67], v[20:21], off offset:-256
	global_load_dwordx4 v[68:71], v[22:23], off offset:192
	global_load_dwordx4 v[78:81], v[24:25], off offset:192
	global_load_dwordx4 v[82:85], v[20:21], off offset:-192
	global_load_dwordx4 v[86:89], v[22:23], off offset:256
	global_load_dwordx4 v[90:93], v[24:25], off offset:256
	global_load_dwordx4 v[94:97], v[20:21], off offset:-128
	global_load_dwordx4 v[98:101], v[22:23], off offset:320
	global_load_dwordx4 v[102:105], v[24:25], off offset:320
	global_load_dwordx4 v[106:109], v[20:21], off offset:-64
	global_load_dwordx4 v[110:113], v[22:23], off offset:384
	global_load_dwordx4 v[114:117], v[24:25], off offset:384
	global_load_dwordx4 v[118:121], v[20:21], off
	global_load_dwordx4 v[122:125], v[22:23], off offset:448
	global_load_dwordx4 v[126:129], v[24:25], off offset:448
	global_load_dwordx4 v[130:133], v[20:21], off offset:64
	global_load_dwordx4 v[134:137], v[22:23], off offset:512
	global_load_dwordx4 v[138:141], v[24:25], off offset:512
	global_load_dwordx4 v[142:145], v[20:21], off offset:128
	global_load_dwordx4 v[146:149], v[22:23], off offset:576
	global_load_dwordx4 v[150:153], v[24:25], off offset:576
	global_load_dwordx4 v[154:157], v[20:21], off offset:192
	global_load_dwordx4 v[158:161], v[22:23], off offset:640
	global_load_dwordx4 v[162:165], v[24:25], off offset:640
	global_load_dwordx4 v[170:173], v[20:21], off offset:256
	global_load_dwordx4 v[176:179], v[22:23], off offset:704
	global_load_dwordx4 v[190:193], v[24:25], off offset:704
	global_load_dwordx4 v[196:199], v[20:21], off offset:320
	s_nop 0
	v_add_co_u32_e32 v30, vcc, 0x180, v30
	v_lshl_add_u64 v[18:19], v[18:19], 0, s[36:37]
	s_andn2_b64 vcc, exec, vcc
	s_nop 0
	s_waitcnt vmcnt(33)
	v_mfma_f32_16x16x32_bf16 v[2:5], v[32:35], v[40:43], v[2:5]
	v_mfma_f32_16x16x32_bf16 v[6:9], v[36:39], v[40:43], v[6:9]
	s_nop 0
	s_nop 0
	s_nop 0
	s_nop 0
	s_waitcnt vmcnt(30)
	v_mfma_f32_16x16x32_bf16 v[2:5], v[44:47], v[52:55], v[2:5]
	v_mfma_f32_16x16x32_bf16 v[6:9], v[48:51], v[52:55], v[6:9]
	s_nop 0
	s_nop 0
	s_nop 0
	s_nop 0
	s_waitcnt vmcnt(27)
	v_mfma_f32_16x16x32_bf16 v[2:5], v[56:59], v[64:67], v[2:5]
	v_mfma_f32_16x16x32_bf16 v[6:9], v[60:63], v[64:67], v[6:9]
	s_nop 0
	s_nop 0
	s_nop 0
	s_nop 0
	s_waitcnt vmcnt(24)
	v_mfma_f32_16x16x32_bf16 v[2:5], v[68:71], v[82:85], v[2:5]
	v_mfma_f32_16x16x32_bf16 v[6:9], v[78:81], v[82:85], v[6:9]
	s_nop 0
	s_nop 0
	s_nop 0
	s_nop 0
	s_waitcnt vmcnt(21)
	v_mfma_f32_16x16x32_bf16 v[2:5], v[86:89], v[94:97], v[2:5]
	v_mfma_f32_16x16x32_bf16 v[6:9], v[90:93], v[94:97], v[6:9]
	s_nop 0
	s_nop 0
	s_nop 0
	s_nop 0
	s_waitcnt vmcnt(18)
	v_mfma_f32_16x16x32_bf16 v[2:5], v[98:101], v[106:109], v[2:5]
	v_mfma_f32_16x16x32_bf16 v[6:9], v[102:105], v[106:109], v[6:9]
	s_nop 0
	s_nop 0
	s_nop 0
	s_nop 0
	s_waitcnt vmcnt(15)
	v_mfma_f32_16x16x32_bf16 v[2:5], v[110:113], v[118:121], v[2:5]
	v_mfma_f32_16x16x32_bf16 v[6:9], v[114:117], v[118:121], v[6:9]
	s_nop 0
	s_nop 0
	s_nop 0
	s_nop 0
	s_waitcnt vmcnt(12)
	v_mfma_f32_16x16x32_bf16 v[2:5], v[122:125], v[130:133], v[2:5]
	v_mfma_f32_16x16x32_bf16 v[6:9], v[126:129], v[130:133], v[6:9]
	s_nop 0
	s_nop 0
	s_nop 0
	s_nop 0
	s_waitcnt vmcnt(9)
	v_mfma_f32_16x16x32_bf16 v[2:5], v[134:137], v[142:145], v[2:5]
	v_mfma_f32_16x16x32_bf16 v[6:9], v[138:141], v[142:145], v[6:9]
	s_nop 0
	s_nop 0
	s_nop 0
	s_nop 0
	s_waitcnt vmcnt(6)
	v_mfma_f32_16x16x32_bf16 v[2:5], v[146:149], v[154:157], v[2:5]
	v_mfma_f32_16x16x32_bf16 v[6:9], v[150:153], v[154:157], v[6:9]
	s_nop 0
	s_nop 0
	s_nop 0
	s_nop 0
	s_waitcnt vmcnt(3)
	v_mfma_f32_16x16x32_bf16 v[2:5], v[158:161], v[170:173], v[2:5]
	v_mfma_f32_16x16x32_bf16 v[6:9], v[162:165], v[170:173], v[6:9]
	s_nop 0
	s_nop 0
	s_nop 0
	s_nop 0
	s_nop 0
	s_nop 0
	s_waitcnt vmcnt(0)
	v_mfma_f32_16x16x32_bf16 v[2:5], v[176:179], v[196:199], v[2:5]
	v_mfma_f32_16x16x32_bf16 v[6:9], v[190:193], v[196:199], v[6:9]
	s_cbranch_vccz .LBB0_939
	s_nop 5
	ds_write2_b32 v29, v2, v3 offset1:16
	v_add_u32_e32 v2, 0x400, v29
	ds_write2_b32 v2, v6, v7 offset1:16
	ds_write2_b32 v29, v4, v5 offset0:32 offset1:48
	ds_write2_b32 v2, v8, v9 offset0:32 offset1:48
	s_waitcnt lgkmcnt(0)
	s_barrier
	ds_read2st64_b32 v[2:3], v27 offset1:8
	v_lshl_or_b32 v16, s2, 4, v26
	v_ashrrev_i32_e32 v17, 31, v16
	s_waitcnt lgkmcnt(0)
	v_add_f32_e32 v2, 0, v2
	v_add_f32_e32 v4, v2, v3
	ds_read2st64_b32 v[2:3], v27 offset0:16 offset1:24
	s_waitcnt lgkmcnt(0)
	v_add_f32_e32 v2, v4, v2
	v_add_f32_e32 v4, v2, v3
	ds_read2st64_b32 v[2:3], v27 offset0:32 offset1:40
	s_waitcnt lgkmcnt(0)
	v_add_f32_e32 v2, v4, v2
	v_add_f32_e32 v4, v2, v3
	ds_read2st64_b32 v[2:3], v27 offset0:48 offset1:56
	s_waitcnt lgkmcnt(0)
	v_add_f32_e32 v2, v4, v2
	v_add_f32_e32 v4, v2, v3
	v_lshl_add_u64 v[2:3], v[16:17], 1, v[10:11]
	global_load_ushort v5, v[2:3], off
	s_waitcnt vmcnt(0)
	v_lshlrev_b32_e32 v5, 16, v5
	v_add_f32_e32 v4, v4, v5
	v_add_f32_e32 v4, 0, v4
	v_cvt_pk_bf16_f32 v4, v4, v1
	global_store_short v[2:3], v4, off
	v_lshlrev_b32_e32 v2, 16, v4
	v_mul_f32_e32 v3, v2, v2
	ds_swizzle_b32 v3, v3 offset:swizzle(SWAP,1)
	s_waitcnt lgkmcnt(0)
	v_fmac_f32_e32 v3, v2, v2
	ds_swizzle_b32 v2, v3 offset:swizzle(SWAP,2)
	s_waitcnt lgkmcnt(0)
	v_add_f32_e32 v2, v3, v2
	ds_swizzle_b32 v3, v2 offset:swizzle(SWAP,4)
	s_waitcnt lgkmcnt(0)
	v_add_f32_e32 v2, v2, v3
	ds_swizzle_b32 v3, v2 offset:swizzle(SWAP,8)
	s_and_saveexec_b64 s[12:13], s[38:39]
	s_cbranch_execz .LBB0_937
	s_ashr_i32 s3, s2, 31
	v_lshl_add_u64 v[4:5], s[2:3], 2, v[12:13]
	s_waitcnt lgkmcnt(0)
	v_add_f32_e32 v2, v2, v3
	global_store_dword v[4:5], v2, off
	s_branch .LBB0_937

;     ...
;         const bf16* bp0 = Bt + (size_t)(n0 + fr) * K + k0 + 8 * fq; const bf16* bp1 = Bt + (size_t)(n1 + fr) * K + k0 + 8 * fq; const bf16* bp2 = Bt + (size_t)(n2 + fr) * K + k0 + 8 * fq;
;         f32x4 acc[NB][2];
; #pragma unroll
;         for (int j = 0; j < NB; ++j) { acc[j][0] = (f32x4){0.f, 0.f, 0.f, 0.f}; acc[j][1] = (f32x4){0.f, 0.f, 0.f, 0.f}; }
; #pragma unroll UNR
;         for (int s = 0; s < kper; s += 32) {
;             const bf16x8 a0 = *(const bf16x8*)(ap0 + s), a1 = *(const bf16x8*)(ap1 + s), b0 = *(const bf16x8*)(bp0 + s);
;             acc[0][0] = __builtin_amdgcn_mfma_f32_16x16x32_bf16(a0, b0, acc[0][0], 0, 0, 0); acc[0][1] = __builtin_amdgcn_mfma_f32_16x16x32_bf16(a1, b0, acc[0][1], 0, 0, 0);
;             if constexpr (NB > 1) { const bf16x8 b1 = *(const bf16x8*)(bp1 + s), b2 = *(const bf16x8*)(bp2 + s);
;                 acc[1][0] = __builtin_amdgcn_mfma_f32_16x16x32_bf16(a0, b1, acc[1][0], 0, 0, 0); acc[1][1] = __builtin_amdgcn_mfma_f32_16x16x32_bf16(a1, b1, acc[1][1], 0, 0, 0);
;                 acc[2][0] = __builtin_amdgcn_mfma_f32_16x16x32_bf16(a0, b2, acc[2][0], 0, 0, 0); acc[2][1] = __builtin_amdgcn_mfma_f32_16x16x32_bf16(a1, b2, acc[2][1], 0, 0, 0); }
;         }
.LBB0_1053:
	global_load_dwordx4 v[78:81], v[2:3], off
	global_load_dwordx4 v[82:85], v[4:5], off
	s_nop 0
	v_ashrrev_i32_e32 v27, 31, v26
	v_lshlrev_b64 v[28:29], 12, v[26:27]
	v_lshl_add_u64 v[32:33], v[6:7], 0, v[28:29]
	global_load_dwordx4 v[86:89], v[32:33], off
	global_load_dwordx4 v[90:93], v[2:3], off offset:64
	global_load_dwordx4 v[94:97], v[32:33], off offset:64
	global_load_dwordx4 v[98:101], v[8:9], off
	global_load_dwordx4 v[102:105], v[2:3], off offset:128
	global_load_dwordx4 v[106:109], v[10:11], off
	s_nop 0
	s_nop 0
	s_nop 0
	s_nop 0
	s_add_i32 s26, s16, s25
	s_add_i32 s10, s24, s25
	s_add_i32 s27, s18, s25
	s_cmpk_lt_i32 s10, 0x240
	s_cselect_b64 s[2:3], -1, 0
	s_and_b64 s[0:1], s[2:3], exec
	s_cselect_b32 s0, s10, s26
	s_cmpk_lt_i32 s27, 0x240
	v_lshl_or_b32 v30, s0, 4, v38
	s_cselect_b64 s[0:1], -1, 0
	v_ashrrev_i32_e32 v31, 31, v30
	s_and_b64 s[10:11], s[0:1], exec
	v_lshlrev_b64 v[28:29], 12, v[30:31]
	s_cselect_b32 s10, s27, s26
	s_nop 0
	s_nop 0
	v_add_u32_e32 v0, 0x400, v41
	s_nop 0
	s_waitcnt vmcnt(5)
	v_mfma_f32_16x16x32_bf16 v[66:69], v[82:85], v[86:89], 0
	s_nop 0
	v_mfma_f32_16x16x32_bf16 v[62:65], v[78:81], v[86:89], 0
	v_lshl_add_u64 v[34:35], v[6:7], 0, v[28:29]
	global_load_dwordx4 v[110:113], v[34:35], off
	v_lshl_or_b32 v28, s10, 4, v38
	v_ashrrev_i32_e32 v29, 31, v28
	v_lshlrev_b64 v[36:37], 12, v[28:29]
	v_lshl_add_u64 v[36:37], v[6:7], 0, v[36:37]
	global_load_dwordx4 v[114:117], v[36:37], off
	global_load_dwordx4 v[118:121], v[32:33], off offset:128
	global_load_dwordx4 v[122:125], v[34:35], off offset:64
	global_load_dwordx4 v[126:129], v[36:37], off offset:64
	global_load_dwordx4 v[130:133], v[2:3], off offset:192
	global_load_dwordx4 v[134:137], v[12:13], off
	global_load_dwordx4 v[138:141], v[32:33], off offset:192
	global_load_dwordx4 v[142:145], v[34:35], off offset:128
	global_load_dwordx4 v[146:149], v[36:37], off offset:128
	global_load_dwordx4 v[150:153], v[2:3], off offset:256
	global_load_dwordx4 v[154:157], v[14:15], off
	global_load_dwordx4 v[158:161], v[32:33], off offset:256
	global_load_dwordx4 v[162:165], v[34:35], off offset:192
	global_load_dwordx4 v[170:173], v[36:37], off offset:192
	global_load_dwordx4 v[176:179], v[34:35], off offset:256
	global_load_dwordx4 v[190:193], v[2:3], off offset:320
	global_load_dwordx4 v[196:199], v[16:17], off
	global_load_dwordx4 v[200:203], v[36:37], off offset:256
	global_load_dwordx4 v[204:207], v[36:37], off offset:320
	global_load_dwordx4 v[208:211], v[32:33], off offset:320
	global_load_dwordx4 v[212:215], v[2:3], off offset:448
	global_load_dwordx4 v[216:219], v[34:35], off offset:320
	global_load_dwordx4 v[228:231], v[2:3], off offset:384
	global_load_dwordx4 v[232:235], v[18:19], off
	global_load_dwordx4 v[236:239], v[32:33], off offset:384
	global_load_dwordx4 v[240:243], v[34:35], off offset:384
	global_load_dwordx4 v[244:247], v[36:37], off offset:384
	global_load_dwordx4 v[248:251], v[32:33], off offset:448
	s_nop 0
	s_nop 0
	s_nop 0
	s_waitcnt vmcnt(32)
	v_mfma_f32_16x16x32_bf16 v[62:65], v[90:93], v[94:97], v[62:65]
	s_mov_b32 s10, 0x2aaaaaab
	s_nop 0
	s_waitcnt vmcnt(31)
	v_mfma_f32_16x16x32_bf16 v[54:57], v[98:101], v[94:97], v[66:69]
	s_nop 0
	s_waitcnt vmcnt(28)
	v_mfma_f32_16x16x32_bf16 v[66:69], v[78:81], v[110:113], 0
	v_mfma_f32_16x16x32_bf16 v[70:73], v[82:85], v[110:113], 0
	s_nop 0
	s_waitcnt vmcnt(27)
	v_mfma_f32_16x16x32_bf16 v[42:45], v[78:81], v[114:117], 0
	global_load_dwordx4 v[78:81], v[20:21], off
	v_mfma_f32_16x16x32_bf16 v[46:49], v[82:85], v[114:117], 0
	global_load_dwordx4 v[82:85], v[34:35], off offset:448
	global_load_dwordx4 v[86:89], v[36:37], off offset:448
	s_nop 0
	s_nop 0
	s_waitcnt vmcnt(29)
	v_mfma_f32_16x16x32_bf16 v[62:65], v[102:105], v[118:121], v[62:65]
	v_mfma_f32_16x16x32_bf16 v[54:57], v[106:109], v[118:121], v[54:57]
	s_nop 0
	s_nop 0
	s_waitcnt vmcnt(28)
	v_mfma_f32_16x16x32_bf16 v[66:69], v[90:93], v[122:125], v[66:69]
	v_mfma_f32_16x16x32_bf16 v[70:73], v[98:101], v[122:125], v[70:73]
	s_nop 0
	s_nop 0
	s_waitcnt vmcnt(27)
	v_mfma_f32_16x16x32_bf16 v[42:45], v[90:93], v[126:129], v[42:45]
	s_nop 0
	v_mfma_f32_16x16x32_bf16 v[46:49], v[98:101], v[126:129], v[46:49]
	s_nop 0
	s_nop 0
	s_nop 0
	s_waitcnt vmcnt(24)
	v_mfma_f32_16x16x32_bf16 v[62:65], v[130:133], v[138:141], v[62:65]
	v_mfma_f32_16x16x32_bf16 v[54:57], v[134:137], v[138:141], v[54:57]
	s_nop 0
	s_nop 0
	s_waitcnt vmcnt(23)
	v_mfma_f32_16x16x32_bf16 v[66:69], v[102:105], v[142:145], v[66:69]
	v_mfma_f32_16x16x32_bf16 v[58:61], v[106:109], v[142:145], v[70:73]
	s_nop 2
	s_nop 0
	s_nop 0
	s_waitcnt vmcnt(22)
;     ...
;         for (int s = 0; s < kper; s += 32) {
;             const bf16x8 a0 = *(const bf16x8*)(ap0 + s), a1 = *(const bf16x8*)(ap1 + s), b0 = *(const bf16x8*)(bp0 + s);
;             acc[0][0] = __builtin_amdgcn_mfma_f32_16x16x32_bf16(a0, b0, acc[0][0], 0, 0, 0); acc[0][1] = __builtin_amdgcn_mfma_f32_16x16x32_bf16(a1, b0, acc[0][1], 0, 0, 0);
;             if constexpr (NB > 1) { const bf16x8 b1 = *(const bf16x8*)(bp1 + s), b2 = *(const bf16x8*)(bp2 + s);
;                 acc[1][0] = __builtin_amdgcn_mfma_f32_16x16x32_bf16(a0, b1, acc[1][0], 0, 0, 0); acc[1][1] = __builtin_amdgcn_mfma_f32_16x16x32_bf16(a1, b1, acc[1][1], 0, 0, 0);
;                 acc[2][0] = __builtin_amdgcn_mfma_f32_16x16x32_bf16(a0, b2, acc[2][0], 0, 0, 0); acc[2][1] = __builtin_amdgcn_mfma_f32_16x16x32_bf16(a1, b2, acc[2][1], 0, 0, 0); }
;         }
; #pragma unroll
;         for (int j = 0; j < NB; ++j)
; #pragma unroll
;             for (int r = 0; r < 4; ++r) { red[j * 4096 + F.wave * 512 + (4 * fq + r) * 16 + fr] = acc[j][0][r]; red[j * 4096 + F.wave * 512 + (16 + 4 * fq + r) * 16 + fr] = acc[j][1][r]; }
;         __syncthreads();
; #pragma unroll
;         for (int j = 0; j < NB; ++j) { if (j == 0 || (j == 1 && v1) || (j == 2 && v2)) { float v = 0.f;
; #pragma unroll
;             for (int w = 0; w < 8; ++w) v += red[j * 4096 + w * 512 + F.tid];
;             fn(F.tid >> 4, (j == 0 ? n0 : (j == 1 ? n1 : n2)) + (F.tid & 15), v * rsd); } }
	v_mfma_f32_16x16x32_bf16 v[42:45], v[102:105], v[146:149], v[42:45]
	s_nop 0
	v_mfma_f32_16x16x32_bf16 v[46:49], v[106:109], v[146:149], v[46:49]
	s_nop 0
	s_nop 0
	s_nop 0
	s_waitcnt vmcnt(19)
	v_mfma_f32_16x16x32_bf16 v[62:65], v[150:153], v[158:161], v[62:65]
	v_mfma_f32_16x16x32_bf16 v[54:57], v[154:157], v[158:161], v[54:57]
	s_nop 0
	s_nop 0
	s_waitcnt vmcnt(18)
	v_mfma_f32_16x16x32_bf16 v[66:69], v[130:133], v[162:165], v[66:69]
	v_mfma_f32_16x16x32_bf16 v[58:61], v[134:137], v[162:165], v[58:61]
	s_nop 0
	s_nop 0
	s_waitcnt vmcnt(17)
	v_mfma_f32_16x16x32_bf16 v[42:45], v[130:133], v[170:173], v[42:45]
	s_nop 0
	v_mfma_f32_16x16x32_bf16 v[46:49], v[134:137], v[170:173], v[46:49]
	s_nop 0
	s_nop 0
	s_nop 0
	s_waitcnt vmcnt(16)
	v_mfma_f32_16x16x32_bf16 v[66:69], v[150:153], v[176:179], v[66:69]
	v_mfma_f32_16x16x32_bf16 v[50:53], v[154:157], v[176:179], v[58:61]
	s_nop 2
	s_nop 0
	s_nop 0
	s_waitcnt vmcnt(13)
	v_mfma_f32_16x16x32_bf16 v[42:45], v[150:153], v[200:203], v[42:45]
	s_nop 0
	v_mfma_f32_16x16x32_bf16 v[46:49], v[154:157], v[200:203], v[46:49]
	s_nop 0
	s_nop 0
	s_nop 0
	s_waitcnt vmcnt(11)
	v_mfma_f32_16x16x32_bf16 v[62:65], v[190:193], v[208:211], v[62:65]
	v_mfma_f32_16x16x32_bf16 v[54:57], v[196:199], v[208:211], v[54:57]
	s_nop 0
	s_nop 0
	s_waitcnt vmcnt(9)
	v_mfma_f32_16x16x32_bf16 v[66:69], v[190:193], v[216:219], v[66:69]
	v_mfma_f32_16x16x32_bf16 v[50:53], v[196:199], v[216:219], v[50:53]
	s_nop 0
	v_mfma_f32_16x16x32_bf16 v[46:49], v[196:199], v[204:207], v[46:49]
	s_nop 0
	v_mfma_f32_16x16x32_bf16 v[42:45], v[190:193], v[204:207], v[42:45]
	s_nop 0
	s_nop 0
	s_nop 0
	s_waitcnt vmcnt(6)
	v_mfma_f32_16x16x32_bf16 v[62:65], v[228:231], v[236:239], v[62:65]
	v_mfma_f32_16x16x32_bf16 v[54:57], v[232:235], v[236:239], v[54:57]
	s_nop 0
	s_nop 0
	s_waitcnt vmcnt(5)
	v_mfma_f32_16x16x32_bf16 v[66:69], v[228:231], v[240:243], v[66:69]
	v_mfma_f32_16x16x32_bf16 v[50:53], v[232:235], v[240:243], v[50:53]
	s_nop 0
	s_nop 0
	s_waitcnt vmcnt(4)
	v_mfma_f32_16x16x32_bf16 v[42:45], v[228:231], v[244:247], v[42:45]
	s_nop 0
	s_nop 0
	s_nop 0
	v_mfma_f32_16x16x32_bf16 v[46:49], v[232:235], v[244:247], v[46:49]
	s_nop 0
	v_add_u32_e32 v36, 0x4400, v41
	s_nop 0
	s_waitcnt vmcnt(3)
	v_mfma_f32_16x16x32_bf16 v[62:65], v[212:215], v[248:251], v[62:65]
	s_nop 0
	s_waitcnt vmcnt(2)
	v_mfma_f32_16x16x32_bf16 v[54:57], v[78:81], v[248:251], v[54:57]
	s_nop 5
	ds_write2_b32 v41, v62, v63 offset1:16
	s_nop 0
	ds_write2_b32 v0, v54, v55 offset1:16
	ds_write2_b32 v41, v64, v65 offset0:32 offset1:48
	ds_write2_b32 v0, v56, v57 offset0:32 offset1:48
	s_nop 0
	s_waitcnt vmcnt(1)
	v_mfma_f32_16x16x32_bf16 v[54:57], v[212:215], v[82:85], v[66:69]
	v_add_u32_e32 v0, 0x4000, v41
	v_mfma_f32_16x16x32_bf16 v[32:35], v[78:81], v[82:85], v[50:53]
	s_nop 5
	ds_write2_b32 v0, v54, v55 offset1:16
	s_nop 0
	ds_write2_b32 v36, v32, v33 offset1:16
	ds_write2_b32 v0, v56, v57 offset0:32 offset1:48
	ds_write2_b32 v36, v34, v35 offset0:32 offset1:48
	s_nop 0
	s_waitcnt vmcnt(0)
	v_mfma_f32_16x16x32_bf16 v[32:35], v[212:215], v[86:89], v[42:45]
	v_add_u32_e32 v0, 0x8000, v41
	v_mfma_f32_16x16x32_bf16 v[42:45], v[78:81], v[86:89], v[46:49]
	s_nop 5
	ds_write2_b32 v0, v32, v33 offset1:16
	v_add_u32_e32 v32, 0x8400, v41
	ds_write2_b32 v32, v42, v43 offset1:16
	ds_write2_b32 v0, v34, v35 offset0:32 offset1:48
	ds_write2_b32 v32, v44, v45 offset0:32 offset1:48
	s_waitcnt lgkmcnt(0)
	s_barrier
	ds_read2st64_b32 v[32:33], v40 offset1:8
	ds_read2st64_b32 v[34:35], v40 offset0:16 offset1:24
	ds_read2st64_b32 v[36:37], v40 offset0:32 offset1:40
	s_waitcnt lgkmcnt(2)
	v_add_f32_e32 v0, 0, v32
	v_add_f32_e32 v0, v0, v33
	ds_read2st64_b32 v[32:33], v40 offset0:48 offset1:56
	s_waitcnt lgkmcnt(2)
	v_add_f32_e32 v0, v0, v34
	v_add_f32_e32 v0, v0, v35
	s_waitcnt lgkmcnt(1)
	v_add_f32_e32 v0, v0, v36
	v_add_f32_e32 v0, v0, v37
	s_waitcnt lgkmcnt(0)
	v_add_f32_e32 v0, v0, v32
	v_add_f32_e32 v0, v0, v33
	v_mul_f32_e32 v34, v39, v0
	v_cvt_pk_bf16_f32 v0, v34, v1
	v_lshl_add_u64 v[32:33], v[26:27], 1, v[22:23]
	global_store_short v[32:33], v0, off
	v_mul_hi_i32 v0, v26, s10
	v_lshrrev_b32_e32 v27, 31, v0
	v_ashrrev_i32_e32 v0, 9, v0
	v_add_u32_e32 v32, v0, v27
	s_movk_i32 s10, 0xf400
	v_mad_i32_i24 v0, v32, s10, v26
	s_movk_i32 s10, 0x3ff
	v_cmp_lt_u32_e32 vcc, s10, v0
	s_and_saveexec_b64 s[10:11], vcc
	s_cbranch_execnz .LBB0_1056
	s_or_b64 exec, exec, s[10:11]
	s_andn2_b64 vcc, exec, s[2:3]
	s_cbranch_vccz .LBB0_1057

;     ...
;         const bf16* bp0 = Bt + (size_t)(n0 + fr) * K + k0 + 8 * fq; const bf16* bp1 = Bt + (size_t)(n1 + fr) * K + k0 + 8 * fq; const bf16* bp2 = Bt + (size_t)(n2 + fr) * K + k0 + 8 * fq;
;         f32x4 acc[NB][2];
; #pragma unroll
;         for (int j = 0; j < NB; ++j) { acc[j][0] = (f32x4){0.f, 0.f, 0.f, 0.f}; acc[j][1] = (f32x4){0.f, 0.f, 0.f, 0.f}; }
; #pragma unroll UNR
;         for (int s = 0; s < kper; s += 32) {
;             const bf16x8 a0 = *(const bf16x8*)(ap0 + s), a1 = *(const bf16x8*)(ap1 + s), b0 = *(const bf16x8*)(bp0 + s);
;             acc[0][0] = __builtin_amdgcn_mfma_f32_16x16x32_bf16(a0, b0, acc[0][0], 0, 0, 0); acc[0][1] = __builtin_amdgcn_mfma_f32_16x16x32_bf16(a1, b0, acc[0][1], 0, 0, 0);
;             if constexpr (NB > 1) { const bf16x8 b1 = *(const bf16x8*)(bp1 + s), b2 = *(const bf16x8*)(bp2 + s);
;                 acc[1][0] = __builtin_amdgcn_mfma_f32_16x16x32_bf16(a0, b1, acc[1][0], 0, 0, 0); acc[1][1] = __builtin_amdgcn_mfma_f32_16x16x32_bf16(a1, b1, acc[1][1], 0, 0, 0);
;                 acc[2][0] = __builtin_amdgcn_mfma_f32_16x16x32_bf16(a0, b2, acc[2][0], 0, 0, 0); acc[2][1] = __builtin_amdgcn_mfma_f32_16x16x32_bf16(a1, b2, acc[2][1], 0, 0, 0); }
;         }
; #pragma unroll
;         for (int j = 0; j < NB; ++j)
; #pragma unroll
;             for (int r = 0; r < 4; ++r) { red[j * 4096 + F.wave * 512 + (4 * fq + r) * 16 + fr] = acc[j][0][r]; red[j * 4096 + F.wave * 512 + (16 + 4 * fq + r) * 16 + fr] = acc[j][1][r]; }
;         __syncthreads();
; #pragma unroll
;         for (int j = 0; j < NB; ++j) { if (j == 0 || (j == 1 && v1) || (j == 2 && v2)) { float v = 0.f;
; #pragma unroll
;             for (int w = 0; w < 8; ++w) v += red[j * 4096 + w * 512 + F.tid];
;             fn(F.tid >> 4, (j == 0 ? n0 : (j == 1 ? n1 : n2)) + (F.tid & 15), v * rsd); } }
;         __syncthreads();
;     }
; }
.LBB0_1337:
	v_ashrrev_i32_e32 v19, 31, v18
	v_lshlrev_b64 v[22:23], 11, v[18:19]
	v_lshl_add_u64 v[42:43], v[6:7], 0, v[22:23]
	global_load_dwordx4 v[30:33], v[2:3], off
	global_load_dwordx4 v[34:37], v[4:5], off
	global_load_dwordx4 v[38:41], v[42:43], off
	global_load_dwordx4 v[44:47], v[2:3], off offset:64
	global_load_dwordx4 v[48:51], v[10:11], off
	global_load_dwordx4 v[52:55], v[42:43], off offset:64
	global_load_dwordx4 v[56:59], v[2:3], off offset:128
	global_load_dwordx4 v[60:63], v[12:13], off
	global_load_dwordx4 v[64:67], v[42:43], off offset:128
	global_load_dwordx4 v[68:71], v[2:3], off offset:192
	global_load_dwordx4 v[78:81], v[14:15], off
	global_load_dwordx4 v[82:85], v[42:43], off offset:192
	s_nop 0
	s_nop 0
	s_nop 0
	v_add_u32_e32 v21, 0x400, v20
	s_nop 0
	s_waitcnt vmcnt(9)
	v_mfma_f32_16x16x32_bf16 v[22:25], v[30:33], v[38:41], 0
	v_mfma_f32_16x16x32_bf16 v[26:29], v[34:37], v[38:41], 0
	s_nop 0
	s_nop 0
	s_nop 0
	s_nop 0
	s_waitcnt vmcnt(6)
	v_mfma_f32_16x16x32_bf16 v[22:25], v[44:47], v[52:55], v[22:25]
	v_mfma_f32_16x16x32_bf16 v[26:29], v[48:51], v[52:55], v[26:29]
	s_nop 0
	s_nop 0
	s_nop 0
	s_nop 0
	s_waitcnt vmcnt(3)
	v_mfma_f32_16x16x32_bf16 v[22:25], v[56:59], v[64:67], v[22:25]
	v_mfma_f32_16x16x32_bf16 v[26:29], v[60:63], v[64:67], v[26:29]
	s_nop 0
	s_nop 0
	s_nop 0
	s_nop 0
	s_waitcnt vmcnt(0)
	v_mfma_f32_16x16x32_bf16 v[22:25], v[68:71], v[82:85], v[22:25]
	s_nop 7
	ds_write2_b32 v20, v22, v23 offset1:16
	v_mfma_f32_16x16x32_bf16 v[26:29], v[78:81], v[82:85], v[26:29]
	s_nop 7
	ds_write2_b32 v21, v26, v27 offset1:16
	ds_write2_b32 v20, v24, v25 offset0:32 offset1:48
	ds_write2_b32 v21, v28, v29 offset0:32 offset1:48
	s_waitcnt lgkmcnt(0)
	s_barrier
	ds_read2st64_b32 v[22:23], v0 offset1:8
	s_waitcnt lgkmcnt(0)
	v_add_f32_e32 v21, 0, v22
	v_add_f32_e32 v21, v21, v23
	ds_read2st64_b32 v[22:23], v0 offset0:16 offset1:24
	s_waitcnt lgkmcnt(0)
	v_add_f32_e32 v21, v21, v22
	v_add_f32_e32 v21, v21, v23
	ds_read2st64_b32 v[22:23], v0 offset0:32 offset1:40
	s_waitcnt lgkmcnt(0)
	v_add_f32_e32 v21, v21, v22
	v_add_f32_e32 v21, v21, v23
	ds_read2st64_b32 v[22:23], v0 offset0:48 offset1:56
	s_waitcnt lgkmcnt(0)
	v_add_f32_e32 v21, v21, v22
	v_add_f32_e32 v21, v21, v23
	v_lshl_add_u64 v[22:23], v[18:19], 1, v[8:9]
	global_load_ushort v19, v[22:23], off
	s_waitcnt vmcnt(0)
	v_lshlrev_b32_e32 v19, 16, v19
	v_add_f32_e32 v19, v21, v19
	v_add_f32_e32 v19, 0, v19
	v_cvt_pk_bf16_f32 v19, v19, v1
	global_store_short v[22:23], v19, off
	v_lshlrev_b32_e32 v19, 16, v19
	v_mul_f32_e32 v21, v19, v19
	ds_swizzle_b32 v21, v21 offset:swizzle(SWAP,1)
	s_waitcnt lgkmcnt(0)
	v_fmac_f32_e32 v21, v19, v19
	ds_swizzle_b32 v19, v21 offset:swizzle(SWAP,2)
	s_waitcnt lgkmcnt(0)
	v_add_f32_e32 v19, v21, v19
	ds_swizzle_b32 v21, v19 offset:swizzle(SWAP,4)
	s_waitcnt lgkmcnt(0)
	v_add_f32_e32 v19, v19, v21
	ds_swizzle_b32 v21, v19 offset:swizzle(SWAP,8)
	s_and_saveexec_b64 s[12:13], vcc
	s_cbranch_execz .LBB0_1336
	s_waitcnt lgkmcnt(0)
	v_add_f32_e32 v19, v19, v21
	global_store_dword v[16:17], v19, off
	s_branch .LBB0_1336

;     ...
;         const bf16* bp0 = Bt + (size_t)(n0 + fr) * K + k0 + 8 * fq; const bf16* bp1 = Bt + (size_t)(n1 + fr) * K + k0 + 8 * fq; const bf16* bp2 = Bt + (size_t)(n2 + fr) * K + k0 + 8 * fq;
;         f32x4 acc[NB][2];
; #pragma unroll
;         for (int j = 0; j < NB; ++j) { acc[j][0] = (f32x4){0.f, 0.f, 0.f, 0.f}; acc[j][1] = (f32x4){0.f, 0.f, 0.f, 0.f}; }
; #pragma unroll UNR
;         for (int s = 0; s < kper; s += 32) {
;             const bf16x8 a0 = *(const bf16x8*)(ap0 + s), a1 = *(const bf16x8*)(ap1 + s), b0 = *(const bf16x8*)(bp0 + s);
;             acc[0][0] = __builtin_amdgcn_mfma_f32_16x16x32_bf16(a0, b0, acc[0][0], 0, 0, 0); acc[0][1] = __builtin_amdgcn_mfma_f32_16x16x32_bf16(a1, b0, acc[0][1], 0, 0, 0);
;             if constexpr (NB > 1) { const bf16x8 b1 = *(const bf16x8*)(bp1 + s), b2 = *(const bf16x8*)(bp2 + s);
;                 acc[1][0] = __builtin_amdgcn_mfma_f32_16x16x32_bf16(a0, b1, acc[1][0], 0, 0, 0); acc[1][1] = __builtin_amdgcn_mfma_f32_16x16x32_bf16(a1, b1, acc[1][1], 0, 0, 0);
;                 acc[2][0] = __builtin_amdgcn_mfma_f32_16x16x32_bf16(a0, b2, acc[2][0], 0, 0, 0); acc[2][1] = __builtin_amdgcn_mfma_f32_16x16x32_bf16(a1, b2, acc[2][1], 0, 0, 0); }
;         }
.LBB0_1446:
	s_add_i32 s24, s25, s20
	s_add_i32 s27, s17, s25
	s_cmpk_lt_i32 s24, 0x300
	s_cselect_b32 s10, s24, s25
	s_lshl_b32 s26, s10, 4
	s_cmpk_lt_i32 s27, 0x300
	s_cselect_b64 s[10:11], -1, 0
	s_and_b64 s[28:29], s[10:11], exec
	s_cselect_b32 s25, s27, s25
	s_lshl_b32 s25, s25, 4
	v_or_b32_e32 v26, s26, v30
	v_add_u32_e32 v24, s16, v30
	v_ashrrev_i32_e32 v27, 31, v26
	v_or_b32_e32 v28, s25, v30
	v_ashrrev_i32_e32 v25, 31, v24
	v_lshlrev_b64 v[26:27], 12, v[26:27]
	v_ashrrev_i32_e32 v29, 31, v28
	v_lshlrev_b64 v[24:25], 12, v[24:25]
	v_lshlrev_b64 v[34:35], 12, v[28:29]
	v_lshl_add_u64 v[26:27], v[6:7], 0, v[26:27]
	v_lshl_add_u64 v[28:29], v[6:7], 0, v[24:25]
	v_lshl_add_u64 v[24:25], v[6:7], 0, v[34:35]
	global_load_dwordx4 v[54:57], v[2:3], off
	global_load_dwordx4 v[62:65], v[4:5], off
	global_load_dwordx4 v[66:69], v[28:29], off
	global_load_dwordx4 v[70:73], v[26:27], off
	global_load_dwordx4 v[78:81], v[24:25], off
	global_load_dwordx4 v[82:85], v[2:3], off offset:64
	global_load_dwordx4 v[86:89], v[8:9], off
	global_load_dwordx4 v[90:93], v[28:29], off offset:64
	global_load_dwordx4 v[94:97], v[26:27], off offset:64
	global_load_dwordx4 v[98:101], v[24:25], off offset:64
	global_load_dwordx4 v[102:105], v[2:3], off offset:128
	global_load_dwordx4 v[106:109], v[10:11], off
	global_load_dwordx4 v[110:113], v[28:29], off offset:128
	global_load_dwordx4 v[114:117], v[26:27], off offset:128
	global_load_dwordx4 v[118:121], v[24:25], off offset:128
	global_load_dwordx4 v[122:125], v[2:3], off offset:192
	global_load_dwordx4 v[126:129], v[12:13], off
	global_load_dwordx4 v[130:133], v[28:29], off offset:192
	global_load_dwordx4 v[134:137], v[26:27], off offset:192
	global_load_dwordx4 v[138:141], v[24:25], off offset:192
	global_load_dwordx4 v[142:145], v[2:3], off offset:256
	global_load_dwordx4 v[146:149], v[14:15], off
	global_load_dwordx4 v[150:153], v[28:29], off offset:256
	global_load_dwordx4 v[154:157], v[26:27], off offset:256
	global_load_dwordx4 v[158:161], v[24:25], off offset:256
	global_load_dwordx4 v[162:165], v[2:3], off offset:320
	global_load_dwordx4 v[170:173], v[16:17], off
	global_load_dwordx4 v[176:179], v[28:29], off offset:320
	global_load_dwordx4 v[190:193], v[26:27], off offset:320
	global_load_dwordx4 v[196:199], v[24:25], off offset:320
	global_load_dwordx4 v[200:203], v[2:3], off offset:384
	global_load_dwordx4 v[204:207], v[18:19], off
	global_load_dwordx4 v[208:211], v[28:29], off offset:384
	global_load_dwordx4 v[212:215], v[26:27], off offset:384
	global_load_dwordx4 v[216:219], v[24:25], off offset:384
	global_load_dwordx4 v[228:231], v[2:3], off offset:448
	global_load_dwordx4 v[232:235], v[20:21], off
	global_load_dwordx4 v[236:239], v[28:29], off offset:448
	global_load_dwordx4 v[240:243], v[26:27], off offset:448
	global_load_dwordx4 v[244:247], v[24:25], off offset:448
	s_nop 0
	s_nop 0
	s_nop 0
	s_nop 0
	s_nop 0
	s_and_b32 s27, s16, 0xf0
	s_cmpk_lt_u32 s27, 0x80
	s_cselect_b64 vcc, -1, 0
	s_and_b32 s28, s12, 0xffffff80
	s_add_i32 s29, s28, 0x1780
	s_cmpk_gt_i32 s24, 0x2ff
	s_nop 0
	s_waitcnt vmcnt(36)
	v_mfma_f32_16x16x32_bf16 v[58:61], v[54:57], v[70:73], 0
	v_mfma_f32_16x16x32_bf16 v[46:49], v[54:57], v[66:69], 0
	v_mfma_f32_16x16x32_bf16 v[42:45], v[62:65], v[66:69], 0
	v_mfma_f32_16x16x32_bf16 v[50:53], v[62:65], v[70:73], 0
	s_nop 0
	s_waitcnt vmcnt(35)
	v_mfma_f32_16x16x32_bf16 v[34:37], v[54:57], v[78:81], 0
	v_mfma_f32_16x16x32_bf16 v[38:41], v[62:65], v[78:81], 0
	s_nop 0
	s_nop 0
	s_nop 0
	s_nop 0
	s_waitcnt vmcnt(32)
	v_mfma_f32_16x16x32_bf16 v[46:49], v[82:85], v[90:93], v[46:49]
	v_mfma_f32_16x16x32_bf16 v[42:45], v[86:89], v[90:93], v[42:45]
	s_nop 0
	s_nop 0
	s_nop 0
	s_waitcnt vmcnt(31)
	v_mfma_f32_16x16x32_bf16 v[58:61], v[82:85], v[94:97], v[58:61]
	v_mfma_f32_16x16x32_bf16 v[50:53], v[86:89], v[94:97], v[50:53]
	s_nop 0
	s_waitcnt vmcnt(30)
	v_mfma_f32_16x16x32_bf16 v[34:37], v[82:85], v[98:101], v[34:37]
	v_mfma_f32_16x16x32_bf16 v[38:41], v[86:89], v[98:101], v[38:41]
	s_nop 0
	s_nop 0
	s_nop 0
	s_nop 0
	s_waitcnt vmcnt(27)
	v_mfma_f32_16x16x32_bf16 v[46:49], v[102:105], v[110:113], v[46:49]
	v_mfma_f32_16x16x32_bf16 v[42:45], v[106:109], v[110:113], v[42:45]
	s_nop 0
	s_nop 0
	s_nop 0
	s_waitcnt vmcnt(26)
	v_mfma_f32_16x16x32_bf16 v[58:61], v[102:105], v[114:117], v[58:61]
	v_mfma_f32_16x16x32_bf16 v[50:53], v[106:109], v[114:117], v[50:53]
	s_nop 0
	s_waitcnt vmcnt(25)
	v_mfma_f32_16x16x32_bf16 v[34:37], v[102:105], v[118:121], v[34:37]
	v_mfma_f32_16x16x32_bf16 v[38:41], v[106:109], v[118:121], v[38:41]
	s_nop 0
	s_nop 0
	s_nop 0
	s_nop 0
	s_waitcnt vmcnt(22)
	v_mfma_f32_16x16x32_bf16 v[46:49], v[122:125], v[130:133], v[46:49]
	v_mfma_f32_16x16x32_bf16 v[42:45], v[126:129], v[130:133], v[42:45]
	s_nop 0
	s_nop 0
	s_nop 0
	s_waitcnt vmcnt(21)
	v_mfma_f32_16x16x32_bf16 v[58:61], v[122:125], v[134:137], v[58:61]
	v_mfma_f32_16x16x32_bf16 v[50:53], v[126:129], v[134:137], v[50:53]
	s_nop 0
	s_waitcnt vmcnt(20)
;     ...
;         for (int s = 0; s < kper; s += 32) {
;             const bf16x8 a0 = *(const bf16x8*)(ap0 + s), a1 = *(const bf16x8*)(ap1 + s), b0 = *(const bf16x8*)(bp0 + s);
;             acc[0][0] = __builtin_amdgcn_mfma_f32_16x16x32_bf16(a0, b0, acc[0][0], 0, 0, 0); acc[0][1] = __builtin_amdgcn_mfma_f32_16x16x32_bf16(a1, b0, acc[0][1], 0, 0, 0);
;             if constexpr (NB > 1) { const bf16x8 b1 = *(const bf16x8*)(bp1 + s), b2 = *(const bf16x8*)(bp2 + s);
;                 acc[1][0] = __builtin_amdgcn_mfma_f32_16x16x32_bf16(a0, b1, acc[1][0], 0, 0, 0); acc[1][1] = __builtin_amdgcn_mfma_f32_16x16x32_bf16(a1, b1, acc[1][1], 0, 0, 0);
;                 acc[2][0] = __builtin_amdgcn_mfma_f32_16x16x32_bf16(a0, b2, acc[2][0], 0, 0, 0); acc[2][1] = __builtin_amdgcn_mfma_f32_16x16x32_bf16(a1, b2, acc[2][1], 0, 0, 0); }
;         }
; #pragma unroll
;         for (int j = 0; j < NB; ++j)
; #pragma unroll
;             for (int r = 0; r < 4; ++r) { red[j * 4096 + F.wave * 512 + (4 * fq + r) * 16 + fr] = acc[j][0][r]; red[j * 4096 + F.wave * 512 + (16 + 4 * fq + r) * 16 + fr] = acc[j][1][r]; }
;         __syncthreads();
; #pragma unroll
;         for (int j = 0; j < NB; ++j) { if (j == 0 || (j == 1 && v1) || (j == 2 && v2)) { float v = 0.f;
; #pragma unroll
;             for (int w = 0; w < 8; ++w) v += red[j * 4096 + w * 512 + F.tid];
;             fn(F.tid >> 4, (j == 0 ? n0 : (j == 1 ? n1 : n2)) + (F.tid & 15), v * rsd); } }
	v_mfma_f32_16x16x32_bf16 v[34:37], v[122:125], v[138:141], v[34:37]
	v_mfma_f32_16x16x32_bf16 v[38:41], v[126:129], v[138:141], v[38:41]
	s_nop 0
	s_nop 0
	s_nop 0
	s_nop 0
	s_waitcnt vmcnt(17)
	v_mfma_f32_16x16x32_bf16 v[46:49], v[142:145], v[150:153], v[46:49]
	v_mfma_f32_16x16x32_bf16 v[42:45], v[146:149], v[150:153], v[42:45]
	s_nop 0
	s_nop 0
	s_nop 0
	s_waitcnt vmcnt(16)
	v_mfma_f32_16x16x32_bf16 v[58:61], v[142:145], v[154:157], v[58:61]
	v_mfma_f32_16x16x32_bf16 v[50:53], v[146:149], v[154:157], v[50:53]
	s_nop 0
	s_waitcnt vmcnt(15)
	v_mfma_f32_16x16x32_bf16 v[34:37], v[142:145], v[158:161], v[34:37]
	v_mfma_f32_16x16x32_bf16 v[38:41], v[146:149], v[158:161], v[38:41]
	s_nop 0
	s_nop 0
	s_nop 0
	s_nop 0
	s_waitcnt vmcnt(12)
	v_mfma_f32_16x16x32_bf16 v[46:49], v[162:165], v[176:179], v[46:49]
	v_mfma_f32_16x16x32_bf16 v[42:45], v[170:173], v[176:179], v[42:45]
	s_nop 0
	s_nop 0
	s_nop 0
	s_waitcnt vmcnt(11)
	v_mfma_f32_16x16x32_bf16 v[58:61], v[162:165], v[190:193], v[58:61]
	v_mfma_f32_16x16x32_bf16 v[50:53], v[170:173], v[190:193], v[50:53]
	s_nop 0
	s_waitcnt vmcnt(10)
	v_mfma_f32_16x16x32_bf16 v[34:37], v[162:165], v[196:199], v[34:37]
	v_mfma_f32_16x16x32_bf16 v[38:41], v[170:173], v[196:199], v[38:41]
	s_nop 0
	s_nop 0
	s_nop 0
	s_nop 0
	s_waitcnt vmcnt(7)
	v_mfma_f32_16x16x32_bf16 v[46:49], v[200:203], v[208:211], v[46:49]
	v_mfma_f32_16x16x32_bf16 v[42:45], v[204:207], v[208:211], v[42:45]
	s_nop 0
	s_nop 0
	s_nop 0
	s_waitcnt vmcnt(6)
	v_mfma_f32_16x16x32_bf16 v[58:61], v[200:203], v[212:215], v[58:61]
	v_mfma_f32_16x16x32_bf16 v[50:53], v[204:207], v[212:215], v[50:53]
	s_nop 0
	s_waitcnt vmcnt(5)
	v_mfma_f32_16x16x32_bf16 v[34:37], v[200:203], v[216:219], v[34:37]
	v_mfma_f32_16x16x32_bf16 v[38:41], v[204:207], v[216:219], v[38:41]
	s_nop 0
	s_nop 0
	s_nop 0
	s_nop 0
	s_waitcnt vmcnt(2)
	v_mfma_f32_16x16x32_bf16 v[46:49], v[228:231], v[236:239], v[46:49]
	v_mfma_f32_16x16x32_bf16 v[42:45], v[232:235], v[236:239], v[42:45]
	s_nop 0
	s_nop 0
	s_nop 0
	s_nop 3
	ds_write2_b32 v32, v46, v47 offset1:16
	s_nop 0
	s_waitcnt vmcnt(1)
	v_mfma_f32_16x16x32_bf16 v[58:61], v[228:231], v[240:243], v[58:61]
	v_mfma_f32_16x16x32_bf16 v[24:27], v[232:235], v[240:243], v[50:53]
	v_add_u32_e32 v28, 0x400, v32
	ds_write2_b32 v28, v42, v43 offset1:16
	ds_write2_b32 v32, v48, v49 offset0:32 offset1:48
	ds_write2_b32 v28, v44, v45 offset0:32 offset1:48
	v_add_u32_e32 v28, 0x4000, v32
	s_nop 0
	s_waitcnt vmcnt(0)
	v_mfma_f32_16x16x32_bf16 v[34:37], v[228:231], v[244:247], v[34:37]
	v_add_u32_e32 v29, 0x4400, v32
	ds_write2_b32 v28, v58, v59 offset1:16
	ds_write2_b32 v29, v24, v25 offset1:16
	ds_write2_b32 v28, v60, v61 offset0:32 offset1:48
	ds_write2_b32 v29, v26, v27 offset0:32 offset1:48
	v_mfma_f32_16x16x32_bf16 v[38:41], v[232:235], v[244:247], v[38:41]
	v_add_u32_e32 v24, 0x8000, v32
	v_add_u32_e32 v25, 0x8400, v32
	ds_write2_b32 v24, v34, v35 offset1:16
	s_nop 4
	ds_write2_b32 v25, v38, v39 offset1:16
	ds_write2_b32 v24, v36, v37 offset0:32 offset1:48
	ds_write2_b32 v25, v40, v41 offset0:32 offset1:48
	s_waitcnt lgkmcnt(0)
	s_barrier
	ds_read2st64_b32 v[24:25], v0 offset1:8
	s_waitcnt lgkmcnt(0)
	v_add_f32_e32 v24, 0, v24
	v_add_f32_e32 v26, v24, v25
	ds_read2st64_b32 v[24:25], v0 offset0:16 offset1:24
	s_waitcnt lgkmcnt(0)
	v_add_f32_e32 v24, v26, v24
	v_add_f32_e32 v26, v24, v25
	ds_read2st64_b32 v[24:25], v0 offset0:32 offset1:40
	s_waitcnt lgkmcnt(0)
	v_add_f32_e32 v24, v26, v24
	v_add_f32_e32 v26, v24, v25
	ds_read2st64_b32 v[24:25], v0 offset0:48 offset1:56
	s_waitcnt lgkmcnt(0)
	v_add_f32_e32 v24, v26, v24
	v_add_f32_e32 v24, v24, v25
	v_mul_f32_e32 v25, v31, v24
	v_or_b32_e32 v24, s27, v30
	v_or_b32_e32 v26, s28, v24
	v_add_u32_e32 v24, s29, v24
	v_cndmask_b32_e32 v24, v24, v26, vcc
	v_cvt_pk_bf16_f32 v26, v25, v1
	v_ashrrev_i32_e32 v25, 31, v24
	v_lshl_add_u64 v[24:25], v[24:25], 1, v[22:23]
	global_store_short v[24:25], v26, off
	s_cbranch_scc1 .LBB0_1448
	ds_read2st64_b32 v[24:25], v0 offset0:64 offset1:72
	s_and_b32 s26, s26, 0xf0
	s_cmpk_lt_u32 s26, 0x80
	s_cselect_b64 vcc, -1, 0
	s_waitcnt lgkmcnt(0)
	v_add_f32_e32 v24, 0, v24
	v_add_f32_e32 v26, v24, v25
	ds_read2st64_b32 v[24:25], v0 offset0:80 offset1:88
	s_waitcnt lgkmcnt(0)
	v_add_f32_e32 v24, v26, v24
	v_add_f32_e32 v26, v24, v25
	ds_read2st64_b32 v[24:25], v0 offset0:96 offset1:104
	s_waitcnt lgkmcnt(0)
	v_add_f32_e32 v24, v26, v24
	v_add_f32_e32 v26, v24, v25
	ds_read2st64_b32 v[24:25], v0 offset0:112 offset1:120
	s_waitcnt lgkmcnt(0)
	v_add_f32_e32 v24, v26, v24
	v_add_f32_e32 v24, v24, v25
	v_mul_f32_e32 v25, v31, v24
	v_or_b32_e32 v24, s26, v30
	s_add_i32 s26, s19, s12
	s_and_b32 s26, s26, 0xffffff80
	v_or_b32_e32 v26, s26, v24
	s_addk_i32 s26, 0x1780
	v_add_u32_e32 v24, s26, v24
	v_cndmask_b32_e32 v24, v24, v26, vcc
	v_cvt_pk_bf16_f32 v26, v25, v1
	v_ashrrev_i32_e32 v25, 31, v24
	v_lshl_add_u64 v[24:25], v[24:25], 1, v[22:23]
	global_store_short v[24:25], v26, off
